# v57 plus MoBA gather deal: on an empty queue read all eight queue counters once and skip to the next non-empty queue (or leave) instead of probing the remaining queues one atomic at a time
# speedup vs baseline: 1.0046x; 1.0032x over previous
; __device__ __forceinline__ void moba_gather(const bf16* __restrict__ Z, const bf16* __restrict__ ZT, const unsigned* __restrict__ SEL, bf16* __restrict__ PO, float* __restrict__ PLSE, unsigned* qctr, LAS unsigned char* lds) {
;     ...
;         if (tid == 0) { unsigned hs = *hsp, kk = 0u;
;             while (hs < 8u) { kk = __hip_atomic_fetch_add(qctr + ((hx + hs) & 7u), 1u, __ATOMIC_RELAXED, __HIP_MEMORY_SCOPE_AGENT); if (kk < (unsigned)MOBA_ITEMS_PER_HEAD) break; ++hs; }
;             *hsp = hs; *itp = (hs < 8u) ? (kk * 8u + ((hx + hs) & 7u)) : 0x7fffffffu; }
.LBB0_1673:
	s_or_b64 exec, exec, s[38:39]
	s_waitcnt vmcnt(0)
	v_readfirstlane_b32 s2, v5
	s_mov_b64 s[36:37], -1
	s_mov_b64 s[38:39], -1
	v_add_u32_e32 v202, s2, v4
	s_movk_i32 s2, 0x61
	v_cmp_lt_u32_e32 vcc, s2, v202
	s_and_saveexec_b64 s[40:41], vcc
	s_cbranch_execz .LBB0_1670
	v_mov_b32_e32 v226, 0
	v_readfirstlane_b32 s100, v200
	global_load_dwordx4 v[228:231], v226, s[28:29] offset:2048 sc1
	global_load_dwordx4 v[232:235], v226, s[28:29] offset:2064 sc1
	s_mov_b32 s101, 0
	s_waitcnt vmcnt(0)
	v_readfirstlane_b32 s2, v228
	s_nop 1
	s_cmpk_lt_u32 s2, 0x62
	s_cselect_b32 s2, 0x1, 0
	s_or_b32 s101, s101, s2
	v_readfirstlane_b32 s2, v229
	s_nop 1
	s_cmpk_lt_u32 s2, 0x62
	s_cselect_b32 s2, 0x2, 0
	s_or_b32 s101, s101, s2
	v_readfirstlane_b32 s2, v230
	s_nop 1
	s_cmpk_lt_u32 s2, 0x62
	s_cselect_b32 s2, 0x4, 0
	s_or_b32 s101, s101, s2
	v_readfirstlane_b32 s2, v231
	s_nop 1
	s_cmpk_lt_u32 s2, 0x62
	s_cselect_b32 s2, 0x8, 0
	s_or_b32 s101, s101, s2
	v_readfirstlane_b32 s2, v232
	s_nop 1
	s_cmpk_lt_u32 s2, 0x62
	s_cselect_b32 s2, 0x10, 0
	s_or_b32 s101, s101, s2
	v_readfirstlane_b32 s2, v233
	s_nop 1
	s_cmpk_lt_u32 s2, 0x62
	s_cselect_b32 s2, 0x20, 0
	s_or_b32 s101, s101, s2
	v_readfirstlane_b32 s2, v234
	s_nop 1
	s_cmpk_lt_u32 s2, 0x62
	s_cselect_b32 s2, 0x40, 0
	s_or_b32 s101, s101, s2
	v_readfirstlane_b32 s2, v235
	s_nop 1
	s_cmpk_lt_u32 s2, 0x62
	s_cselect_b32 s2, 0x80, 0
	s_or_b32 s101, s101, s2
	s_lshl_b32 s2, s101, 8
	s_or_b32 s101, s101, s2
	s_and_b32 s2, s21, 7
	s_lshr_b32 s101, s101, s2
	s_and_b32 s101, s101, 0xff
	s_lshl_b32 s2, 2, s100
	s_add_i32 s2, s2, -1
	s_andn2_b32 s101, s101, s2
	s_ff1_i32_b32 s2, s101
	s_cmp_eq_u32 s101, 0
	s_cselect_b32 s2, 8, s2
	v_mov_b32_e32 v4, s2
	v_cmp_lt_u32_e32 vcc, 7, v4
	s_xor_b64 s[38:39], exec, -1
	s_orn2_b64 s[36:37], vcc, exec
	s_branch .LBB0_1670
